# grid barrier: blocks that are not the last of their XCD back off ~0.6us before their first poll of the release counter (less polling traffic while stragglers finish)
# baseline (speedup 1.0000x reference)
.LBB0_119:
	s_or_b64 exec, exec, s[6:7]
	v_cvt_f32_u32_e32 v4, v2
	s_waitcnt vmcnt(0)
	v_readfirstlane_b32 s4, v3
	v_sub_u32_e32 v3, 0, v2
	v_rcp_iflag_f32_e32 v4, v4
	v_add_u32_e32 v5, s4, v1
	v_mul_f32_e32 v4, 0x4f7ffffe, v4
	v_cvt_u32_f32_e32 v4, v4
	v_mul_lo_u32 v1, v3, v4
	v_mul_hi_u32 v1, v4, v1
	v_add_u32_e32 v1, v4, v1
	v_mul_hi_u32 v1, v5, v1
	v_mul_lo_u32 v3, v1, v2
	v_sub_u32_e32 v3, v5, v3
	v_add_u32_e32 v4, 1, v1
	v_cmp_ge_u32_e32 vcc, v3, v2
	s_nop 1
	v_cndmask_b32_e32 v1, v1, v4, vcc
	v_sub_u32_e32 v4, v3, v2
	v_cndmask_b32_e32 v3, v3, v4, vcc
	v_add_u32_e32 v4, 1, v1
	v_cmp_ge_u32_e32 vcc, v3, v2
	v_add_u32_e32 v3, 1, v5
	s_nop 0
	v_cndmask_b32_e32 v1, v1, v4, vcc
	v_mul_lo_u32 v4, v2, v1
	v_add_u32_e32 v2, v4, v2
	v_cmp_ne_u32_e32 vcc, v3, v2
	s_cbranch_vccnz .Lxb_bo_1
	buffer_wbl2 sc1
	s_waitcnt vmcnt(0) lgkmcnt(0)
	v_mov_b32_e32 v4, 0x3400
	v_mov_b32_e32 v5, 1
	global_atomic_add v4, v5, s[2:3]
	s_nop 4
	s_branch .Lxb_nl_1
.Lxb_bo_1:
	s_sleep 24

.LBB0_279:
	s_or_b64 exec, exec, s[6:7]
	v_cvt_f32_u32_e32 v4, v2
	s_waitcnt vmcnt(0)
	v_readfirstlane_b32 s4, v3
	v_sub_u32_e32 v3, 0, v2
	v_rcp_iflag_f32_e32 v4, v4
	v_add_u32_e32 v5, s4, v0
	v_mul_f32_e32 v4, 0x4f7ffffe, v4
	v_cvt_u32_f32_e32 v4, v4
	v_mul_lo_u32 v0, v3, v4
	v_mul_hi_u32 v0, v4, v0
	v_add_u32_e32 v0, v4, v0
	v_mul_hi_u32 v0, v5, v0
	v_mul_lo_u32 v3, v0, v2
	v_sub_u32_e32 v3, v5, v3
	v_add_u32_e32 v4, 1, v0
	v_cmp_ge_u32_e32 vcc, v3, v2
	s_nop 1
	v_cndmask_b32_e32 v0, v0, v4, vcc
	v_sub_u32_e32 v4, v3, v2
	v_cndmask_b32_e32 v3, v3, v4, vcc
	v_add_u32_e32 v4, 1, v0
	v_cmp_ge_u32_e32 vcc, v3, v2
	v_add_u32_e32 v3, 1, v5
	s_nop 0
	v_cndmask_b32_e32 v0, v0, v4, vcc
	v_mul_lo_u32 v4, v2, v0
	v_add_u32_e32 v2, v4, v2
	v_cmp_ne_u32_e32 vcc, v3, v2
	s_cbranch_vccnz .Lxb_bo_3
	buffer_wbl2 sc1
	s_waitcnt vmcnt(0) lgkmcnt(0)
	v_mov_b32_e32 v4, 0x3400
	v_mov_b32_e32 v5, 1
	global_atomic_add v4, v5, s[2:3]
	s_nop 4
	s_branch .Lxb_nl_3
